# GEMM K-loops: matrix-segment end barrier signalled 2 MFMAs early (last 2 MFMAs issue behind it at priority 2)
# speedup vs baseline: 1.0057x; 1.0057x over previous
.LBB0_126:
	ds_read_b128 v[148:151], v159
	ds_read_b128 v[152:155], v159 offset:1024
	ds_read_b128 v[162:165], v159 offset:2048
	ds_read_b128 v[166:169], v159 offset:3072
	ds_read_b128 v[170:173], v160
	ds_read_b128 v[174:177], v160 offset:1024
	ds_read_b128 v[178:181], v160 offset:2048
	ds_read_b128 v[182:185], v160 offset:3072
	s_add_u32 s34, s30, 0xfffc0080
	s_addc_u32 s35, s31, -1
	s_cmp_eq_u32 s72, 12
	s_cselect_b32 s37, s5, s35
	s_cselect_b32 s36, s38, s34
	s_cselect_b32 s35, s39, s71
	s_cselect_b32 s34, s44, s45
	v_lshl_add_u64 v[156:157], s[30:31], 0, v[140:141]
	s_add_i32 m0, s48, 0xc000
	ds_read_b128 v[186:189], v161
	ds_read_b128 v[190:193], v161 offset:1024
	ds_read_b128 v[194:197], v161 offset:2048
	ds_read_b128 v[198:201], v161 offset:3072
	ds_read_b128 v[202:205], v161 offset:4096
	ds_read_b128 v[206:209], v161 offset:5120
	ds_read_b128 v[210:213], v161 offset:6144
	ds_read_b128 v[214:217], v161 offset:7168
	global_load_lds_dwordx4 v[156:157], off
	v_lshl_add_u64 v[156:157], s[30:31], 0, v[142:143]
	s_add_i32 m0, s48, 0xe000
	s_nop 0
	global_load_lds_dwordx4 v[156:157], off
	s_waitcnt vmcnt(8)
	s_waitcnt lgkmcnt(0)
	s_barrier
	s_setprio 1
	s_waitcnt lgkmcnt(0)
	v_mfma_f32_16x16x32_bf16 v[126:129], v[148:151], v[186:189], v[126:129]
	v_mfma_f32_16x16x32_bf16 v[122:125], v[162:165], v[186:189], v[122:125]
	v_mfma_f32_16x16x32_bf16 v[110:113], v[148:151], v[194:197], v[110:113]
	v_mfma_f32_16x16x32_bf16 v[106:109], v[162:165], v[194:197], v[106:109]
	v_mfma_f32_16x16x32_bf16 v[94:97], v[148:151], v[202:205], v[94:97]
	v_mfma_f32_16x16x32_bf16 v[90:93], v[162:165], v[202:205], v[90:93]
	v_mfma_f32_16x16x32_bf16 v[78:81], v[148:151], v[210:213], v[78:81]
	v_mfma_f32_16x16x32_bf16 v[74:77], v[162:165], v[210:213], v[74:77]
	v_mfma_f32_16x16x32_bf16 v[126:129], v[152:155], v[190:193], v[126:129]
	v_mfma_f32_16x16x32_bf16 v[122:125], v[166:169], v[190:193], v[122:125]
	v_mfma_f32_16x16x32_bf16 v[110:113], v[152:155], v[198:201], v[110:113]
	v_mfma_f32_16x16x32_bf16 v[106:109], v[166:169], v[198:201], v[106:109]
	v_mfma_f32_16x16x32_bf16 v[94:97], v[152:155], v[206:209], v[94:97]
	v_mfma_f32_16x16x32_bf16 v[90:93], v[166:169], v[206:209], v[90:93]
	v_mfma_f32_16x16x32_bf16 v[78:81], v[152:155], v[214:217], v[78:81]
	v_mfma_f32_16x16x32_bf16 v[74:77], v[166:169], v[214:217], v[74:77]
	s_setprio 0
	s_setprio 1
	v_mfma_f32_16x16x32_bf16 v[118:121], v[170:173], v[186:189], v[118:121]
	v_mfma_f32_16x16x32_bf16 v[114:117], v[178:181], v[186:189], v[114:117]
	v_mfma_f32_16x16x32_bf16 v[102:105], v[170:173], v[194:197], v[102:105]
	v_mfma_f32_16x16x32_bf16 v[98:101], v[178:181], v[194:197], v[98:101]
	v_mfma_f32_16x16x32_bf16 v[86:89], v[170:173], v[202:205], v[86:89]
	v_mfma_f32_16x16x32_bf16 v[82:85], v[178:181], v[202:205], v[82:85]
	v_mfma_f32_16x16x32_bf16 v[70:73], v[170:173], v[210:213], v[70:73]
	v_mfma_f32_16x16x32_bf16 v[66:69], v[178:181], v[210:213], v[66:69]
	v_mfma_f32_16x16x32_bf16 v[118:121], v[174:177], v[190:193], v[118:121]
	v_mfma_f32_16x16x32_bf16 v[114:117], v[182:185], v[190:193], v[114:117]
	v_mfma_f32_16x16x32_bf16 v[102:105], v[174:177], v[198:201], v[102:105]
	v_mfma_f32_16x16x32_bf16 v[98:101], v[182:185], v[198:201], v[98:101]
	v_mfma_f32_16x16x32_bf16 v[86:89], v[174:177], v[206:209], v[86:89]
	v_mfma_f32_16x16x32_bf16 v[82:85], v[182:185], v[206:209], v[82:85]
	s_setprio 2
	s_barrier
	v_mfma_f32_16x16x32_bf16 v[70:73], v[174:177], v[214:217], v[70:73]
	v_mfma_f32_16x16x32_bf16 v[66:69], v[182:185], v[214:217], v[66:69]
	s_setprio 0
	s_add_i32 s73, s65, s47
	v_lshl_add_u64 v[156:157], s[34:35], 0, v[132:133]
	s_mov_b32 m0, s73
	ds_read_b128 v[186:189], v161 offset:16384
	ds_read_b128 v[190:193], v161 offset:17408
	ds_read_b128 v[194:197], v161 offset:18432
	ds_read_b128 v[198:201], v161 offset:19456
	ds_read_b128 v[202:205], v161 offset:20480
	ds_read_b128 v[206:209], v161 offset:21504
	ds_read_b128 v[210:213], v161 offset:22528
	ds_read_b128 v[214:217], v161 offset:23552
	global_load_lds_dwordx4 v[156:157], off
	s_add_i32 m0, s73, 0x2000
	s_add_u32 s74, s34, 0x40000
	v_lshl_add_u64 v[218:219], s[34:35], 0, v[136:137]
	s_addc_u32 s75, s35, 0
	s_add_i32 s73, s66, s47
	global_load_lds_dwordx4 v[218:219], off
	v_lshl_add_u64 v[220:221], s[74:75], 0, v[132:133]
	s_mov_b32 m0, s73
	v_lshl_add_u64 v[222:223], s[36:37], 0, v[134:135]
	global_load_lds_dwordx4 v[220:221], off
	v_lshl_add_u64 v[220:221], s[74:75], 0, v[136:137]
	s_add_i32 m0, s73, 0x2000
	s_nop 0
	global_load_lds_dwordx4 v[220:221], off
	v_lshl_add_u64 v[220:221], s[36:37], 0, v[130:131]
	s_mov_b32 m0, s48
	s_nop 0
	global_load_lds_dwordx4 v[220:221], off
	s_mov_b32 m0, s49
	s_nop 0
	global_load_lds_dwordx4 v[222:223], off
	s_waitcnt vmcnt(8)
	s_waitcnt lgkmcnt(0)
	s_barrier
	s_setprio 1
	s_waitcnt lgkmcnt(0)
	v_mfma_f32_16x16x32_bf16 v[62:65], v[148:151], v[186:189], v[62:65]
	v_mfma_f32_16x16x32_bf16 v[58:61], v[162:165], v[186:189], v[58:61]
	v_mfma_f32_16x16x32_bf16 v[46:49], v[148:151], v[194:197], v[46:49]
	v_mfma_f32_16x16x32_bf16 v[42:45], v[162:165], v[194:197], v[42:45]
	v_mfma_f32_16x16x32_bf16 v[30:33], v[148:151], v[202:205], v[30:33]
	v_mfma_f32_16x16x32_bf16 v[26:29], v[162:165], v[202:205], v[26:29]
	v_mfma_f32_16x16x32_bf16 v[14:17], v[148:151], v[210:213], v[14:17]
	v_mfma_f32_16x16x32_bf16 v[10:13], v[162:165], v[210:213], v[10:13]
	v_mfma_f32_16x16x32_bf16 v[62:65], v[152:155], v[190:193], v[62:65]
	v_mfma_f32_16x16x32_bf16 v[58:61], v[166:169], v[190:193], v[58:61]
	v_mfma_f32_16x16x32_bf16 v[46:49], v[152:155], v[198:201], v[46:49]
	v_mfma_f32_16x16x32_bf16 v[42:45], v[166:169], v[198:201], v[42:45]
	v_mfma_f32_16x16x32_bf16 v[30:33], v[152:155], v[206:209], v[30:33]
	v_mfma_f32_16x16x32_bf16 v[26:29], v[166:169], v[206:209], v[26:29]
	v_mfma_f32_16x16x32_bf16 v[14:17], v[152:155], v[214:217], v[14:17]
	v_mfma_f32_16x16x32_bf16 v[10:13], v[166:169], v[214:217], v[10:13]
	s_setprio 0
	s_setprio 1
	v_mfma_f32_16x16x32_bf16 v[54:57], v[170:173], v[186:189], v[54:57]
	v_mfma_f32_16x16x32_bf16 v[50:53], v[178:181], v[186:189], v[50:53]
	v_mfma_f32_16x16x32_bf16 v[38:41], v[170:173], v[194:197], v[38:41]
	v_mfma_f32_16x16x32_bf16 v[34:37], v[178:181], v[194:197], v[34:37]
	v_mfma_f32_16x16x32_bf16 v[22:25], v[170:173], v[202:205], v[22:25]
	v_mfma_f32_16x16x32_bf16 v[18:21], v[178:181], v[202:205], v[18:21]
	v_mfma_f32_16x16x32_bf16 v[6:9], v[170:173], v[210:213], v[6:9]
	v_mfma_f32_16x16x32_bf16 v[2:5], v[178:181], v[210:213], v[2:5]
	v_mfma_f32_16x16x32_bf16 v[54:57], v[174:177], v[190:193], v[54:57]
	v_mfma_f32_16x16x32_bf16 v[50:53], v[182:185], v[190:193], v[50:53]
	v_mfma_f32_16x16x32_bf16 v[38:41], v[174:177], v[198:201], v[38:41]
	v_mfma_f32_16x16x32_bf16 v[34:37], v[182:185], v[198:201], v[34:37]
	v_mfma_f32_16x16x32_bf16 v[22:25], v[174:177], v[206:209], v[22:25]
	v_mfma_f32_16x16x32_bf16 v[18:21], v[182:185], v[206:209], v[18:21]
	s_setprio 2
	s_barrier
	v_mfma_f32_16x16x32_bf16 v[6:9], v[174:177], v[214:217], v[6:9]
	v_mfma_f32_16x16x32_bf16 v[2:5], v[182:185], v[214:217], v[2:5]
	s_setprio 0
	s_add_i32 s73, 0, 0x18000
	v_add_u32_e32 v138, s73, v158
	s_add_i32 s74, 0, 0x1c000
	ds_read_b128 v[148:151], v138
	ds_read_b128 v[152:155], v138 offset:1024
	ds_read_b128 v[162:165], v138 offset:2048
	ds_read_b128 v[166:169], v138 offset:3072
	v_add_u32_e32 v138, s74, v158
	ds_read_b128 v[170:173], v138
	ds_read_b128 v[174:177], v138 offset:1024
	ds_read_b128 v[178:181], v138 offset:2048
	ds_read_b128 v[182:185], v138 offset:3072
	s_add_u32 s36, s36, 0x40000
	s_addc_u32 s37, s37, 0
	s_mov_b32 m0, s50
	v_lshl_add_u64 v[224:225], s[36:37], 0, v[130:131]
	ds_read_b128 v[186:189], v161 offset:32768
	ds_read_b128 v[190:193], v161 offset:33792
	ds_read_b128 v[194:197], v161 offset:34816
	ds_read_b128 v[198:201], v161 offset:35840
	ds_read_b128 v[202:205], v161 offset:36864
	ds_read_b128 v[206:209], v161 offset:37888
	ds_read_b128 v[210:213], v161 offset:38912
	ds_read_b128 v[214:217], v161 offset:39936
	global_load_lds_dwordx4 v[224:225], off
	v_lshl_add_u64 v[224:225], s[36:37], 0, v[134:135]
	s_mov_b32 m0, s51
	s_nop 0
	global_load_lds_dwordx4 v[224:225], off
	s_waitcnt vmcnt(8)
	s_waitcnt lgkmcnt(0)
	s_barrier
	s_setprio 1
	s_waitcnt lgkmcnt(0)
	v_mfma_f32_16x16x32_bf16 v[126:129], v[148:151], v[186:189], v[126:129]
	v_mfma_f32_16x16x32_bf16 v[122:125], v[162:165], v[186:189], v[122:125]
	v_mfma_f32_16x16x32_bf16 v[110:113], v[148:151], v[194:197], v[110:113]
	v_mfma_f32_16x16x32_bf16 v[106:109], v[162:165], v[194:197], v[106:109]
	v_mfma_f32_16x16x32_bf16 v[94:97], v[148:151], v[202:205], v[94:97]
	v_mfma_f32_16x16x32_bf16 v[90:93], v[162:165], v[202:205], v[90:93]
	v_mfma_f32_16x16x32_bf16 v[78:81], v[148:151], v[210:213], v[78:81]
	v_mfma_f32_16x16x32_bf16 v[74:77], v[162:165], v[210:213], v[74:77]
	v_mfma_f32_16x16x32_bf16 v[126:129], v[152:155], v[190:193], v[126:129]
	v_mfma_f32_16x16x32_bf16 v[122:125], v[166:169], v[190:193], v[122:125]
	v_mfma_f32_16x16x32_bf16 v[110:113], v[152:155], v[198:201], v[110:113]
	v_mfma_f32_16x16x32_bf16 v[106:109], v[166:169], v[198:201], v[106:109]
	v_mfma_f32_16x16x32_bf16 v[94:97], v[152:155], v[206:209], v[94:97]
	v_mfma_f32_16x16x32_bf16 v[90:93], v[166:169], v[206:209], v[90:93]
	v_mfma_f32_16x16x32_bf16 v[78:81], v[152:155], v[214:217], v[78:81]
	v_mfma_f32_16x16x32_bf16 v[74:77], v[166:169], v[214:217], v[74:77]
	s_setprio 0
	s_setprio 1
	v_mfma_f32_16x16x32_bf16 v[118:121], v[170:173], v[186:189], v[118:121]
	v_mfma_f32_16x16x32_bf16 v[114:117], v[178:181], v[186:189], v[114:117]
	v_mfma_f32_16x16x32_bf16 v[102:105], v[170:173], v[194:197], v[102:105]
	v_mfma_f32_16x16x32_bf16 v[98:101], v[178:181], v[194:197], v[98:101]
	v_mfma_f32_16x16x32_bf16 v[86:89], v[170:173], v[202:205], v[86:89]
	v_mfma_f32_16x16x32_bf16 v[82:85], v[178:181], v[202:205], v[82:85]
	v_mfma_f32_16x16x32_bf16 v[70:73], v[170:173], v[210:213], v[70:73]
	v_mfma_f32_16x16x32_bf16 v[66:69], v[178:181], v[210:213], v[66:69]
	v_mfma_f32_16x16x32_bf16 v[118:121], v[174:177], v[190:193], v[118:121]
	v_mfma_f32_16x16x32_bf16 v[114:117], v[182:185], v[190:193], v[114:117]
	v_mfma_f32_16x16x32_bf16 v[102:105], v[174:177], v[198:201], v[102:105]
	v_mfma_f32_16x16x32_bf16 v[98:101], v[182:185], v[198:201], v[98:101]
	v_mfma_f32_16x16x32_bf16 v[86:89], v[174:177], v[206:209], v[86:89]
	v_mfma_f32_16x16x32_bf16 v[82:85], v[182:185], v[206:209], v[82:85]
	s_setprio 2
	s_barrier
	v_mfma_f32_16x16x32_bf16 v[70:73], v[174:177], v[214:217], v[70:73]
	v_mfma_f32_16x16x32_bf16 v[66:69], v[182:185], v[214:217], v[66:69]
	s_setprio 0
	s_add_i32 s36, s73, s47
	v_lshl_add_u64 v[156:157], v[156:157], 0, s[14:15]
	s_mov_b32 m0, s36
	ds_read_b128 v[186:189], v161 offset:49152
	ds_read_b128 v[190:193], v161 offset:50176
	ds_read_b128 v[194:197], v161 offset:51200
	ds_read_b128 v[198:201], v161 offset:52224
	ds_read_b128 v[202:205], v161 offset:53248
	ds_read_b128 v[206:209], v161 offset:54272
	ds_read_b128 v[210:213], v161 offset:55296
	ds_read_b128 v[214:217], v161 offset:56320
	global_load_lds_dwordx4 v[156:157], off
	s_add_i32 m0, s36, 0x2000
	s_add_u32 s34, s34, 0x40080
	v_lshl_add_u64 v[156:157], v[218:219], 0, s[14:15]
	s_addc_u32 s35, s35, 0
	s_add_i32 s36, s74, s47
	global_load_lds_dwordx4 v[156:157], off
	v_lshl_add_u64 v[156:157], s[34:35], 0, v[132:133]
	s_mov_b32 m0, s36
	s_nop 0
	global_load_lds_dwordx4 v[156:157], off
	v_lshl_add_u64 v[156:157], s[34:35], 0, v[136:137]
	s_add_i32 m0, s36, 0x2000
	s_nop 0
	global_load_lds_dwordx4 v[156:157], off
	v_lshl_add_u64 v[156:157], v[220:221], 0, s[14:15]
	s_mov_b32 m0, s62
	s_nop 0
	global_load_lds_dwordx4 v[156:157], off
	v_lshl_add_u64 v[156:157], v[222:223], 0, s[14:15]
	s_mov_b32 m0, s63
	s_nop 0
	global_load_lds_dwordx4 v[156:157], off
	s_waitcnt vmcnt(8)
	s_waitcnt lgkmcnt(0)
	s_barrier
	s_setprio 1
	s_waitcnt lgkmcnt(0)
	v_mfma_f32_16x16x32_bf16 v[62:65], v[148:151], v[186:189], v[62:65]
	v_mfma_f32_16x16x32_bf16 v[58:61], v[162:165], v[186:189], v[58:61]
	v_mfma_f32_16x16x32_bf16 v[46:49], v[148:151], v[194:197], v[46:49]
	v_mfma_f32_16x16x32_bf16 v[42:45], v[162:165], v[194:197], v[42:45]
	v_mfma_f32_16x16x32_bf16 v[30:33], v[148:151], v[202:205], v[30:33]
	v_mfma_f32_16x16x32_bf16 v[26:29], v[162:165], v[202:205], v[26:29]
	v_mfma_f32_16x16x32_bf16 v[14:17], v[148:151], v[210:213], v[14:17]
	v_mfma_f32_16x16x32_bf16 v[10:13], v[162:165], v[210:213], v[10:13]
	v_mfma_f32_16x16x32_bf16 v[62:65], v[152:155], v[190:193], v[62:65]
	v_mfma_f32_16x16x32_bf16 v[58:61], v[166:169], v[190:193], v[58:61]
	v_mfma_f32_16x16x32_bf16 v[46:49], v[152:155], v[198:201], v[46:49]
	v_mfma_f32_16x16x32_bf16 v[42:45], v[166:169], v[198:201], v[42:45]
	v_mfma_f32_16x16x32_bf16 v[30:33], v[152:155], v[206:209], v[30:33]
	v_mfma_f32_16x16x32_bf16 v[26:29], v[166:169], v[206:209], v[26:29]
	v_mfma_f32_16x16x32_bf16 v[14:17], v[152:155], v[214:217], v[14:17]
	v_mfma_f32_16x16x32_bf16 v[10:13], v[166:169], v[214:217], v[10:13]
	s_setprio 0
	s_setprio 1
	v_mfma_f32_16x16x32_bf16 v[54:57], v[170:173], v[186:189], v[54:57]
	v_mfma_f32_16x16x32_bf16 v[50:53], v[178:181], v[186:189], v[50:53]
	v_mfma_f32_16x16x32_bf16 v[38:41], v[170:173], v[194:197], v[38:41]
	v_mfma_f32_16x16x32_bf16 v[34:37], v[178:181], v[194:197], v[34:37]
	v_mfma_f32_16x16x32_bf16 v[22:25], v[170:173], v[202:205], v[22:25]
	v_mfma_f32_16x16x32_bf16 v[18:21], v[178:181], v[202:205], v[18:21]
	v_mfma_f32_16x16x32_bf16 v[6:9], v[170:173], v[210:213], v[6:9]
	v_mfma_f32_16x16x32_bf16 v[2:5], v[178:181], v[210:213], v[2:5]
	v_mfma_f32_16x16x32_bf16 v[54:57], v[174:177], v[190:193], v[54:57]
	v_mfma_f32_16x16x32_bf16 v[50:53], v[182:185], v[190:193], v[50:53]
	v_mfma_f32_16x16x32_bf16 v[38:41], v[174:177], v[198:201], v[38:41]
	v_mfma_f32_16x16x32_bf16 v[34:37], v[182:185], v[198:201], v[34:37]
	v_mfma_f32_16x16x32_bf16 v[22:25], v[174:177], v[206:209], v[22:25]
	v_mfma_f32_16x16x32_bf16 v[18:21], v[182:185], v[206:209], v[18:21]
	s_setprio 2
	s_barrier
	v_mfma_f32_16x16x32_bf16 v[6:9], v[174:177], v[214:217], v[6:9]
	v_mfma_f32_16x16x32_bf16 v[2:5], v[182:185], v[214:217], v[2:5]
	s_setprio 0
	s_add_i32 s72, s72, 2
	s_add_u32 s30, s30, 0x100
	s_addc_u32 s31, s31, 0
	s_add_u32 s45, s45, 0x100
	s_addc_u32 s71, s71, 0
	s_cmp_gt_u32 s72, 13
	s_cbranch_scc0 .LBB0_126
	s_and_b64 vcc, exec, s[18:19]
	s_cbranch_vccz .LBB0_129
	s_barrier

.LBB0_761:
	v_add_u32_e32 v164, s62, v150
	v_add_u32_e32 v180, s63, v150
	s_add_u32 s34, s16, s26
	ds_read_b128 v[152:155], v164
	ds_read_b128 v[156:159], v164 offset:1024
	ds_read_b128 v[160:163], v164 offset:2048
	ds_read_b128 v[164:167], v164 offset:3072
	ds_read_b128 v[168:171], v180
	ds_read_b128 v[172:175], v180 offset:1024
	ds_read_b128 v[176:179], v180 offset:2048
	ds_read_b128 v[180:183], v180 offset:3072
	s_addc_u32 s35, s17, s27
	s_add_u32 s34, s34, 0x100
	s_addc_u32 s35, s35, 0
	s_add_u32 s68, s21, s26
	s_addc_u32 s69, s66, s27
	s_cmpk_eq_i32 s26, 0xf00
	s_cselect_b32 s37, s29, s35
	s_cselect_b32 s36, s28, s34
	s_cselect_b32 s35, s31, s69
	s_cselect_b32 s34, s30, s68
	v_lshl_add_u64 v[216:217], v[146:147], 0, s[26:27]
	s_add_i32 m0, s15, 0xc000
	ds_read_b128 v[184:187], v151
	ds_read_b128 v[188:191], v151 offset:1024
	ds_read_b128 v[192:195], v151 offset:2048
	ds_read_b128 v[196:199], v151 offset:3072
	ds_read_b128 v[200:203], v151 offset:4096
	ds_read_b128 v[204:207], v151 offset:5120
	ds_read_b128 v[208:211], v151 offset:6144
	ds_read_b128 v[212:215], v151 offset:7168
	global_load_lds_dwordx4 v[216:217], off
	v_lshl_add_u64 v[216:217], v[148:149], 0, s[26:27]
	s_add_i32 m0, s15, 0xe000
	s_nop 0
	global_load_lds_dwordx4 v[216:217], off
	s_waitcnt vmcnt(8)
	s_waitcnt lgkmcnt(0)
	s_barrier
	s_setprio 1
	s_waitcnt lgkmcnt(0)
	v_mfma_f32_16x16x32_bf16 v[126:129], v[152:155], v[184:187], v[126:129]
	v_mfma_f32_16x16x32_bf16 v[122:125], v[160:163], v[184:187], v[122:125]
	v_mfma_f32_16x16x32_bf16 v[118:121], v[152:155], v[192:195], v[118:121]
	v_mfma_f32_16x16x32_bf16 v[114:117], v[160:163], v[192:195], v[114:117]
	v_mfma_f32_16x16x32_bf16 v[94:97], v[152:155], v[200:203], v[94:97]
	v_mfma_f32_16x16x32_bf16 v[90:93], v[160:163], v[200:203], v[90:93]
	v_mfma_f32_16x16x32_bf16 v[86:89], v[152:155], v[208:211], v[86:89]
	v_mfma_f32_16x16x32_bf16 v[82:85], v[160:163], v[208:211], v[82:85]
	v_mfma_f32_16x16x32_bf16 v[126:129], v[156:159], v[188:191], v[126:129]
	v_mfma_f32_16x16x32_bf16 v[122:125], v[164:167], v[188:191], v[122:125]
	v_mfma_f32_16x16x32_bf16 v[118:121], v[156:159], v[196:199], v[118:121]
	v_mfma_f32_16x16x32_bf16 v[114:117], v[164:167], v[196:199], v[114:117]
	v_mfma_f32_16x16x32_bf16 v[94:97], v[156:159], v[204:207], v[94:97]
	v_mfma_f32_16x16x32_bf16 v[90:93], v[164:167], v[204:207], v[90:93]
	v_mfma_f32_16x16x32_bf16 v[86:89], v[156:159], v[212:215], v[86:89]
	v_mfma_f32_16x16x32_bf16 v[82:85], v[164:167], v[212:215], v[82:85]
	s_setprio 0
	s_setprio 1
	v_mfma_f32_16x16x32_bf16 v[110:113], v[168:171], v[184:187], v[110:113]
	v_mfma_f32_16x16x32_bf16 v[106:109], v[176:179], v[184:187], v[106:109]
	v_mfma_f32_16x16x32_bf16 v[102:105], v[168:171], v[192:195], v[102:105]
	v_mfma_f32_16x16x32_bf16 v[98:101], v[176:179], v[192:195], v[98:101]
	v_mfma_f32_16x16x32_bf16 v[78:81], v[168:171], v[200:203], v[78:81]
	v_mfma_f32_16x16x32_bf16 v[74:77], v[176:179], v[200:203], v[74:77]
	v_mfma_f32_16x16x32_bf16 v[70:73], v[168:171], v[208:211], v[70:73]
	v_mfma_f32_16x16x32_bf16 v[66:69], v[176:179], v[208:211], v[66:69]
	v_mfma_f32_16x16x32_bf16 v[110:113], v[172:175], v[188:191], v[110:113]
	v_mfma_f32_16x16x32_bf16 v[106:109], v[180:183], v[188:191], v[106:109]
	v_mfma_f32_16x16x32_bf16 v[102:105], v[172:175], v[196:199], v[102:105]
	v_mfma_f32_16x16x32_bf16 v[98:101], v[180:183], v[196:199], v[98:101]
	v_mfma_f32_16x16x32_bf16 v[78:81], v[172:175], v[204:207], v[78:81]
	v_mfma_f32_16x16x32_bf16 v[74:77], v[180:183], v[204:207], v[74:77]
	s_setprio 2
	s_barrier
	v_mfma_f32_16x16x32_bf16 v[70:73], v[172:175], v[212:215], v[70:73]
	v_mfma_f32_16x16x32_bf16 v[66:69], v[180:183], v[212:215], v[66:69]
	s_setprio 0
	s_add_i32 s68, s62, s48
	v_lshl_add_u64 v[216:217], s[34:35], 0, v[132:133]
	s_mov_b32 m0, s68
	ds_read_b128 v[184:187], v151 offset:16384
	ds_read_b128 v[188:191], v151 offset:17408
	ds_read_b128 v[192:195], v151 offset:18432
	ds_read_b128 v[196:199], v151 offset:19456
	ds_read_b128 v[200:203], v151 offset:20480
	ds_read_b128 v[204:207], v151 offset:21504
	ds_read_b128 v[208:211], v151 offset:22528
	ds_read_b128 v[212:215], v151 offset:23552
	global_load_lds_dwordx4 v[216:217], off
	s_add_i32 m0, s68, 0x2000
	s_add_u32 s68, s34, 0x80000
	v_lshl_add_u64 v[218:219], s[34:35], 0, v[136:137]
	s_addc_u32 s69, s35, 0
	s_add_i32 s70, s63, s48
	global_load_lds_dwordx4 v[218:219], off
	v_lshl_add_u64 v[220:221], s[68:69], 0, v[132:133]
	s_mov_b32 m0, s70
	v_lshl_add_u64 v[222:223], s[36:37], 0, v[134:135]
	global_load_lds_dwordx4 v[220:221], off
	v_lshl_add_u64 v[220:221], s[68:69], 0, v[136:137]
	s_add_i32 m0, s70, 0x2000
	s_nop 0
	global_load_lds_dwordx4 v[220:221], off
	v_lshl_add_u64 v[220:221], s[36:37], 0, v[130:131]
	s_mov_b32 m0, s15
	s_nop 0
	global_load_lds_dwordx4 v[220:221], off
	s_mov_b32 m0, s50
	s_nop 0
	global_load_lds_dwordx4 v[222:223], off
	s_waitcnt vmcnt(8)
	s_waitcnt lgkmcnt(0)
	s_barrier
	s_setprio 1
	s_waitcnt lgkmcnt(0)
	v_mfma_f32_16x16x32_bf16 v[62:65], v[152:155], v[184:187], v[62:65]
	v_mfma_f32_16x16x32_bf16 v[58:61], v[160:163], v[184:187], v[58:61]
	v_mfma_f32_16x16x32_bf16 v[54:57], v[152:155], v[192:195], v[54:57]
	v_mfma_f32_16x16x32_bf16 v[50:53], v[160:163], v[192:195], v[50:53]
	v_mfma_f32_16x16x32_bf16 v[30:33], v[152:155], v[200:203], v[30:33]
	v_mfma_f32_16x16x32_bf16 v[26:29], v[160:163], v[200:203], v[26:29]
	v_mfma_f32_16x16x32_bf16 v[22:25], v[152:155], v[208:211], v[22:25]
	v_mfma_f32_16x16x32_bf16 v[18:21], v[160:163], v[208:211], v[18:21]
	v_mfma_f32_16x16x32_bf16 v[62:65], v[156:159], v[188:191], v[62:65]
	v_mfma_f32_16x16x32_bf16 v[58:61], v[164:167], v[188:191], v[58:61]
	v_mfma_f32_16x16x32_bf16 v[54:57], v[156:159], v[196:199], v[54:57]
	v_mfma_f32_16x16x32_bf16 v[50:53], v[164:167], v[196:199], v[50:53]
	v_mfma_f32_16x16x32_bf16 v[30:33], v[156:159], v[204:207], v[30:33]
	v_mfma_f32_16x16x32_bf16 v[26:29], v[164:167], v[204:207], v[26:29]
	v_mfma_f32_16x16x32_bf16 v[22:25], v[156:159], v[212:215], v[22:25]
	v_mfma_f32_16x16x32_bf16 v[18:21], v[164:167], v[212:215], v[18:21]
	s_setprio 0
	s_setprio 1
	v_mfma_f32_16x16x32_bf16 v[46:49], v[168:171], v[184:187], v[46:49]
	v_mfma_f32_16x16x32_bf16 v[42:45], v[176:179], v[184:187], v[42:45]
	v_mfma_f32_16x16x32_bf16 v[38:41], v[168:171], v[192:195], v[38:41]
	v_mfma_f32_16x16x32_bf16 v[34:37], v[176:179], v[192:195], v[34:37]
	v_mfma_f32_16x16x32_bf16 v[14:17], v[168:171], v[200:203], v[14:17]
	v_mfma_f32_16x16x32_bf16 v[10:13], v[176:179], v[200:203], v[10:13]
	v_mfma_f32_16x16x32_bf16 v[6:9], v[168:171], v[208:211], v[6:9]
	v_mfma_f32_16x16x32_bf16 v[2:5], v[176:179], v[208:211], v[2:5]
	v_mfma_f32_16x16x32_bf16 v[46:49], v[172:175], v[188:191], v[46:49]
	v_mfma_f32_16x16x32_bf16 v[42:45], v[180:183], v[188:191], v[42:45]
	v_mfma_f32_16x16x32_bf16 v[38:41], v[172:175], v[196:199], v[38:41]
	v_mfma_f32_16x16x32_bf16 v[34:37], v[180:183], v[196:199], v[34:37]
	v_mfma_f32_16x16x32_bf16 v[14:17], v[172:175], v[204:207], v[14:17]
	v_mfma_f32_16x16x32_bf16 v[10:13], v[180:183], v[204:207], v[10:13]
	s_setprio 2
	s_barrier
	v_mfma_f32_16x16x32_bf16 v[6:9], v[172:175], v[212:215], v[6:9]
	v_mfma_f32_16x16x32_bf16 v[2:5], v[180:183], v[212:215], v[2:5]
	s_setprio 0
	s_add_i32 s68, 0, 0x18000
	s_add_i32 s69, 0, 0x1c000
	v_add_u32_e32 v164, s68, v150
	v_add_u32_e32 v180, s69, v150
	ds_read_b128 v[152:155], v164
	ds_read_b128 v[156:159], v164 offset:1024
	ds_read_b128 v[160:163], v164 offset:2048
	ds_read_b128 v[164:167], v164 offset:3072
	ds_read_b128 v[168:171], v180
	ds_read_b128 v[172:175], v180 offset:1024
	ds_read_b128 v[176:179], v180 offset:2048
	ds_read_b128 v[180:183], v180 offset:3072
	s_add_u32 s36, s36, 0x80000
	s_addc_u32 s37, s37, 0
	s_mov_b32 m0, s51
	v_lshl_add_u64 v[224:225], s[36:37], 0, v[130:131]
	ds_read_b128 v[184:187], v151 offset:32768
	ds_read_b128 v[188:191], v151 offset:33792
	ds_read_b128 v[192:195], v151 offset:34816
	ds_read_b128 v[196:199], v151 offset:35840
	ds_read_b128 v[200:203], v151 offset:36864
	ds_read_b128 v[204:207], v151 offset:37888
	ds_read_b128 v[208:211], v151 offset:38912
	ds_read_b128 v[212:215], v151 offset:39936
	global_load_lds_dwordx4 v[224:225], off
	v_lshl_add_u64 v[224:225], s[36:37], 0, v[134:135]
	s_mov_b32 m0, s57
	s_nop 0
	global_load_lds_dwordx4 v[224:225], off
	s_waitcnt vmcnt(8)
	s_waitcnt lgkmcnt(0)
	s_barrier
	s_setprio 1
	s_waitcnt lgkmcnt(0)
	v_mfma_f32_16x16x32_bf16 v[126:129], v[152:155], v[184:187], v[126:129]
	v_mfma_f32_16x16x32_bf16 v[122:125], v[160:163], v[184:187], v[122:125]
	v_mfma_f32_16x16x32_bf16 v[118:121], v[152:155], v[192:195], v[118:121]
	v_mfma_f32_16x16x32_bf16 v[114:117], v[160:163], v[192:195], v[114:117]
	v_mfma_f32_16x16x32_bf16 v[94:97], v[152:155], v[200:203], v[94:97]
	v_mfma_f32_16x16x32_bf16 v[90:93], v[160:163], v[200:203], v[90:93]
	v_mfma_f32_16x16x32_bf16 v[86:89], v[152:155], v[208:211], v[86:89]
	v_mfma_f32_16x16x32_bf16 v[82:85], v[160:163], v[208:211], v[82:85]
	v_mfma_f32_16x16x32_bf16 v[126:129], v[156:159], v[188:191], v[126:129]
	v_mfma_f32_16x16x32_bf16 v[122:125], v[164:167], v[188:191], v[122:125]
	v_mfma_f32_16x16x32_bf16 v[118:121], v[156:159], v[196:199], v[118:121]
	v_mfma_f32_16x16x32_bf16 v[114:117], v[164:167], v[196:199], v[114:117]
	v_mfma_f32_16x16x32_bf16 v[94:97], v[156:159], v[204:207], v[94:97]
	v_mfma_f32_16x16x32_bf16 v[90:93], v[164:167], v[204:207], v[90:93]
	v_mfma_f32_16x16x32_bf16 v[86:89], v[156:159], v[212:215], v[86:89]
	v_mfma_f32_16x16x32_bf16 v[82:85], v[164:167], v[212:215], v[82:85]
	s_setprio 0
	s_setprio 1
	v_mfma_f32_16x16x32_bf16 v[110:113], v[168:171], v[184:187], v[110:113]
	v_mfma_f32_16x16x32_bf16 v[106:109], v[176:179], v[184:187], v[106:109]
	v_mfma_f32_16x16x32_bf16 v[102:105], v[168:171], v[192:195], v[102:105]
	v_mfma_f32_16x16x32_bf16 v[98:101], v[176:179], v[192:195], v[98:101]
	v_mfma_f32_16x16x32_bf16 v[78:81], v[168:171], v[200:203], v[78:81]
	v_mfma_f32_16x16x32_bf16 v[74:77], v[176:179], v[200:203], v[74:77]
	v_mfma_f32_16x16x32_bf16 v[70:73], v[168:171], v[208:211], v[70:73]
	v_mfma_f32_16x16x32_bf16 v[66:69], v[176:179], v[208:211], v[66:69]
	v_mfma_f32_16x16x32_bf16 v[110:113], v[172:175], v[188:191], v[110:113]
	v_mfma_f32_16x16x32_bf16 v[106:109], v[180:183], v[188:191], v[106:109]
	v_mfma_f32_16x16x32_bf16 v[102:105], v[172:175], v[196:199], v[102:105]
	v_mfma_f32_16x16x32_bf16 v[98:101], v[180:183], v[196:199], v[98:101]
	v_mfma_f32_16x16x32_bf16 v[78:81], v[172:175], v[204:207], v[78:81]
	v_mfma_f32_16x16x32_bf16 v[74:77], v[180:183], v[204:207], v[74:77]
	s_setprio 2
	s_barrier
	v_mfma_f32_16x16x32_bf16 v[70:73], v[172:175], v[212:215], v[70:73]
	v_mfma_f32_16x16x32_bf16 v[66:69], v[180:183], v[212:215], v[66:69]
	s_setprio 0
	s_add_i32 s36, s68, s48
	v_lshl_add_u64 v[216:217], v[216:217], 0, s[18:19]
	s_mov_b32 m0, s36
	ds_read_b128 v[184:187], v151 offset:49152
	ds_read_b128 v[188:191], v151 offset:50176
	ds_read_b128 v[192:195], v151 offset:51200
	ds_read_b128 v[196:199], v151 offset:52224
	ds_read_b128 v[200:203], v151 offset:53248
	ds_read_b128 v[204:207], v151 offset:54272
	ds_read_b128 v[208:211], v151 offset:55296
	ds_read_b128 v[212:215], v151 offset:56320
	global_load_lds_dwordx4 v[216:217], off
	s_add_i32 m0, s36, 0x2000
	s_add_u32 s34, s34, 0x80080
	v_lshl_add_u64 v[216:217], v[218:219], 0, s[18:19]
	s_addc_u32 s35, s35, 0
	s_add_i32 s36, s69, s48
	global_load_lds_dwordx4 v[216:217], off
	v_lshl_add_u64 v[216:217], s[34:35], 0, v[132:133]
	s_mov_b32 m0, s36
	s_nop 0
	global_load_lds_dwordx4 v[216:217], off
	v_lshl_add_u64 v[216:217], s[34:35], 0, v[136:137]
	s_add_i32 m0, s36, 0x2000
	s_nop 0
	global_load_lds_dwordx4 v[216:217], off
	v_lshl_add_u64 v[216:217], v[220:221], 0, s[18:19]
	s_mov_b32 m0, s60
	s_nop 0
	global_load_lds_dwordx4 v[216:217], off
	v_lshl_add_u64 v[216:217], v[222:223], 0, s[18:19]
	s_mov_b32 m0, s61
	s_nop 0
	global_load_lds_dwordx4 v[216:217], off
	s_waitcnt vmcnt(8)
	s_waitcnt lgkmcnt(0)
	s_barrier
	s_setprio 1
	s_waitcnt lgkmcnt(0)
	v_mfma_f32_16x16x32_bf16 v[62:65], v[152:155], v[184:187], v[62:65]
	v_mfma_f32_16x16x32_bf16 v[58:61], v[160:163], v[184:187], v[58:61]
	v_mfma_f32_16x16x32_bf16 v[54:57], v[152:155], v[192:195], v[54:57]
	v_mfma_f32_16x16x32_bf16 v[50:53], v[160:163], v[192:195], v[50:53]
	v_mfma_f32_16x16x32_bf16 v[30:33], v[152:155], v[200:203], v[30:33]
	v_mfma_f32_16x16x32_bf16 v[26:29], v[160:163], v[200:203], v[26:29]
	v_mfma_f32_16x16x32_bf16 v[22:25], v[152:155], v[208:211], v[22:25]
	v_mfma_f32_16x16x32_bf16 v[18:21], v[160:163], v[208:211], v[18:21]
	v_mfma_f32_16x16x32_bf16 v[62:65], v[156:159], v[188:191], v[62:65]
	v_mfma_f32_16x16x32_bf16 v[58:61], v[164:167], v[188:191], v[58:61]
	v_mfma_f32_16x16x32_bf16 v[54:57], v[156:159], v[196:199], v[54:57]
	v_mfma_f32_16x16x32_bf16 v[50:53], v[164:167], v[196:199], v[50:53]
	v_mfma_f32_16x16x32_bf16 v[30:33], v[156:159], v[204:207], v[30:33]
	v_mfma_f32_16x16x32_bf16 v[26:29], v[164:167], v[204:207], v[26:29]
	v_mfma_f32_16x16x32_bf16 v[22:25], v[156:159], v[212:215], v[22:25]
	v_mfma_f32_16x16x32_bf16 v[18:21], v[164:167], v[212:215], v[18:21]
	s_setprio 0
	s_setprio 1
	v_mfma_f32_16x16x32_bf16 v[46:49], v[168:171], v[184:187], v[46:49]
	v_mfma_f32_16x16x32_bf16 v[42:45], v[176:179], v[184:187], v[42:45]
	v_mfma_f32_16x16x32_bf16 v[38:41], v[168:171], v[192:195], v[38:41]
	v_mfma_f32_16x16x32_bf16 v[34:37], v[176:179], v[192:195], v[34:37]
	v_mfma_f32_16x16x32_bf16 v[14:17], v[168:171], v[200:203], v[14:17]
	v_mfma_f32_16x16x32_bf16 v[10:13], v[176:179], v[200:203], v[10:13]
	v_mfma_f32_16x16x32_bf16 v[6:9], v[168:171], v[208:211], v[6:9]
	v_mfma_f32_16x16x32_bf16 v[2:5], v[176:179], v[208:211], v[2:5]
	v_mfma_f32_16x16x32_bf16 v[46:49], v[172:175], v[188:191], v[46:49]
	v_mfma_f32_16x16x32_bf16 v[42:45], v[180:183], v[188:191], v[42:45]
	v_mfma_f32_16x16x32_bf16 v[38:41], v[172:175], v[196:199], v[38:41]
	v_mfma_f32_16x16x32_bf16 v[34:37], v[180:183], v[196:199], v[34:37]
	v_mfma_f32_16x16x32_bf16 v[14:17], v[172:175], v[204:207], v[14:17]
	v_mfma_f32_16x16x32_bf16 v[10:13], v[180:183], v[204:207], v[10:13]
	s_setprio 2
	s_barrier
	v_mfma_f32_16x16x32_bf16 v[6:9], v[172:175], v[212:215], v[6:9]
	v_mfma_f32_16x16x32_bf16 v[2:5], v[180:183], v[212:215], v[2:5]
	s_setprio 0
	s_add_i32 s67, s67, 2
	s_add_u32 s26, s26, 0x100
	s_addc_u32 s27, s27, 0
	s_cmp_gt_u32 s67, 29
	s_cbranch_scc0 .LBB0_761
	s_add_u32 s26, s21, 0xffffff00
	s_addc_u32 s27, s66, -1
	s_andn2_b64 vcc, exec, s[6:7]
	s_cbranch_vccnz .LBB0_753
	v_mov_b32_e32 v2, 0
	s_mov_b32 s8, s64
	s_mov_b32 s14, s20
	s_mov_b64 s[26:27], s[24:25]
	s_mov_b64 s[16:17], s[22:23]
	s_mov_b32 s59, s65
	v_mov_b32_e32 v3, v2
	v_mov_b32_e32 v4, v2
	v_mov_b32_e32 v5, v2
	v_mov_b32_e32 v6, v2
	v_mov_b32_e32 v7, v2
	v_mov_b32_e32 v8, v2
	v_mov_b32_e32 v9, v2
	v_mov_b32_e32 v10, v2
	v_mov_b32_e32 v11, v2
	v_mov_b32_e32 v12, v2
	v_mov_b32_e32 v13, v2
	v_mov_b32_e32 v14, v2
	v_mov_b32_e32 v15, v2
	v_mov_b32_e32 v16, v2
	v_mov_b32_e32 v17, v2
	v_mov_b32_e32 v34, v2
	v_mov_b32_e32 v35, v2
	v_mov_b32_e32 v36, v2
	v_mov_b32_e32 v37, v2
	v_mov_b32_e32 v38, v2
	v_mov_b32_e32 v39, v2
	v_mov_b32_e32 v40, v2
	v_mov_b32_e32 v41, v2
	v_mov_b32_e32 v42, v2
	v_mov_b32_e32 v43, v2
	v_mov_b32_e32 v44, v2
	v_mov_b32_e32 v45, v2
	v_mov_b32_e32 v46, v2
	v_mov_b32_e32 v47, v2
	v_mov_b32_e32 v48, v2
	v_mov_b32_e32 v49, v2
	v_mov_b32_e32 v18, v2
	v_mov_b32_e32 v19, v2
	v_mov_b32_e32 v20, v2
	v_mov_b32_e32 v21, v2
	v_mov_b32_e32 v22, v2
	v_mov_b32_e32 v23, v2
	v_mov_b32_e32 v24, v2
	v_mov_b32_e32 v25, v2
	v_mov_b32_e32 v26, v2
	v_mov_b32_e32 v27, v2
	v_mov_b32_e32 v28, v2
	v_mov_b32_e32 v29, v2
	v_mov_b32_e32 v30, v2
	v_mov_b32_e32 v31, v2
	v_mov_b32_e32 v32, v2
	v_mov_b32_e32 v33, v2
	v_mov_b32_e32 v50, v2
	v_mov_b32_e32 v51, v2
	v_mov_b32_e32 v52, v2
	v_mov_b32_e32 v53, v2
	v_mov_b32_e32 v54, v2
	v_mov_b32_e32 v55, v2
	v_mov_b32_e32 v56, v2
	v_mov_b32_e32 v57, v2
	v_mov_b32_e32 v58, v2
	v_mov_b32_e32 v59, v2
	v_mov_b32_e32 v60, v2
	v_mov_b32_e32 v61, v2
	v_mov_b32_e32 v62, v2
	v_mov_b32_e32 v63, v2
	v_mov_b32_e32 v64, v2
	v_mov_b32_e32 v65, v2
	v_mov_b32_e32 v66, v2
	v_mov_b32_e32 v67, v2
	v_mov_b32_e32 v68, v2
	v_mov_b32_e32 v69, v2
	v_mov_b32_e32 v70, v2
	v_mov_b32_e32 v71, v2
	v_mov_b32_e32 v72, v2
	v_mov_b32_e32 v73, v2
	v_mov_b32_e32 v74, v2
	v_mov_b32_e32 v75, v2
	v_mov_b32_e32 v76, v2
	v_mov_b32_e32 v77, v2
	v_mov_b32_e32 v78, v2
	v_mov_b32_e32 v79, v2
	v_mov_b32_e32 v80, v2
	v_mov_b32_e32 v81, v2
	v_mov_b32_e32 v98, v2
	v_mov_b32_e32 v99, v2
	v_mov_b32_e32 v100, v2
	v_mov_b32_e32 v101, v2
	v_mov_b32_e32 v102, v2
	v_mov_b32_e32 v103, v2
	v_mov_b32_e32 v104, v2
	v_mov_b32_e32 v105, v2
	v_mov_b32_e32 v106, v2
	v_mov_b32_e32 v107, v2
	v_mov_b32_e32 v108, v2
	v_mov_b32_e32 v109, v2
	v_mov_b32_e32 v110, v2
	v_mov_b32_e32 v111, v2
	v_mov_b32_e32 v112, v2
	v_mov_b32_e32 v113, v2
	v_mov_b32_e32 v82, v2
	v_mov_b32_e32 v83, v2
	v_mov_b32_e32 v84, v2
	v_mov_b32_e32 v85, v2
	v_mov_b32_e32 v86, v2
	v_mov_b32_e32 v87, v2
	v_mov_b32_e32 v88, v2
	v_mov_b32_e32 v89, v2
	v_mov_b32_e32 v90, v2
	v_mov_b32_e32 v91, v2
	v_mov_b32_e32 v92, v2
	v_mov_b32_e32 v93, v2
	v_mov_b32_e32 v94, v2
	v_mov_b32_e32 v95, v2
	v_mov_b32_e32 v96, v2
	v_mov_b32_e32 v97, v2
	v_mov_b32_e32 v114, v2
	v_mov_b32_e32 v115, v2
	v_mov_b32_e32 v116, v2
	v_mov_b32_e32 v117, v2
	v_mov_b32_e32 v118, v2
	v_mov_b32_e32 v119, v2
	v_mov_b32_e32 v120, v2
	v_mov_b32_e32 v121, v2
	v_mov_b32_e32 v122, v2
	v_mov_b32_e32 v123, v2
	v_mov_b32_e32 v124, v2
	v_mov_b32_e32 v125, v2
	v_mov_b32_e32 v126, v2
	v_mov_b32_e32 v127, v2
	v_mov_b32_e32 v128, v2
	v_mov_b32_e32 v129, v2
	s_branch .LBB0_753

.LBB0_965:
	s_cmp_eq_u32 s89, 12
	s_cselect_b64 s[14:15], -1, 0
	s_and_b64 s[14:15], s[14:15], exec
	s_cselect_b32 s15, s54, s88
	s_cselect_b32 s14, s55, s87
	s_add_u32 s90, s12, 0xfffc0080
	s_addc_u32 s91, s13, -1
	s_cmp_eq_u32 s89, 12
	s_cselect_b64 s[42:43], -1, 0
	s_and_b64 s[40:41], s[42:43], exec
	s_cselect_b32 s40, s51, s90
	s_cselect_b32 s41, s50, s91
	s_and_b64 vcc, s[38:39], s[42:43]
	s_and_b64 s[42:43], vcc, exec
	s_cselect_b32 s63, s56, s63
	s_cselect_b32 s64, s86, s64
	s_add_i32 s42, 0, 0x10000
	v_add_u32_e32 v147, s42, v194
	s_add_i32 s43, 0, 0x14000
	ds_read_b128 v[130:133], v147
	ds_read_b128 v[134:137], v147 offset:1024
	ds_read_b128 v[148:151], v147 offset:2048
	ds_read_b128 v[152:155], v147 offset:3072
	v_add_u32_e32 v147, s43, v194
	ds_read_b128 v[156:159], v147
	ds_read_b128 v[160:163], v147 offset:1024
	ds_read_b128 v[164:167], v147 offset:2048
	ds_read_b128 v[168:171], v147 offset:3072
	v_cndmask_b32_e32 v146, v146, v129, vcc
	v_cndmask_b32_e32 v138, v138, v128, vcc
	v_lshl_add_u64 v[228:229], s[12:13], 0, v[144:145]
	s_add_i32 m0, s62, 0xc000
	ds_read_b128 v[196:199], v195
	ds_read_b128 v[200:203], v195 offset:1024
	ds_read_b128 v[204:207], v195 offset:2048
	ds_read_b128 v[208:211], v195 offset:3072
	ds_read_b128 v[212:215], v195 offset:4096
	ds_read_b128 v[216:219], v195 offset:5120
	ds_read_b128 v[220:223], v195 offset:6144
	ds_read_b128 v[224:227], v195 offset:7168
	global_load_lds_dwordx4 v[228:229], off
	v_lshl_add_u64 v[228:229], s[12:13], 0, v[142:143]
	s_add_i32 m0, s62, 0xe000
	s_nop 0
	global_load_lds_dwordx4 v[228:229], off
	s_waitcnt vmcnt(8)
	s_waitcnt lgkmcnt(0)
	s_barrier
	s_setprio 1
	s_waitcnt lgkmcnt(0)
	v_mfma_f32_16x16x32_bf16 v[124:127], v[130:133], v[196:199], v[124:127]
	v_mfma_f32_16x16x32_bf16 v[120:123], v[148:151], v[196:199], v[120:123]
	v_mfma_f32_16x16x32_bf16 v[108:111], v[130:133], v[204:207], v[108:111]
	v_mfma_f32_16x16x32_bf16 v[104:107], v[148:151], v[204:207], v[104:107]
	v_mfma_f32_16x16x32_bf16 v[92:95], v[130:133], v[212:215], v[92:95]
	v_mfma_f32_16x16x32_bf16 v[88:91], v[148:151], v[212:215], v[88:91]
	v_mfma_f32_16x16x32_bf16 v[76:79], v[130:133], v[220:223], v[76:79]
	v_mfma_f32_16x16x32_bf16 v[72:75], v[148:151], v[220:223], v[72:75]
	v_mfma_f32_16x16x32_bf16 v[124:127], v[134:137], v[200:203], v[124:127]
	v_mfma_f32_16x16x32_bf16 v[120:123], v[152:155], v[200:203], v[120:123]
	v_mfma_f32_16x16x32_bf16 v[108:111], v[134:137], v[208:211], v[108:111]
	v_mfma_f32_16x16x32_bf16 v[104:107], v[152:155], v[208:211], v[104:107]
	v_mfma_f32_16x16x32_bf16 v[92:95], v[134:137], v[216:219], v[92:95]
	v_mfma_f32_16x16x32_bf16 v[88:91], v[152:155], v[216:219], v[88:91]
	v_mfma_f32_16x16x32_bf16 v[76:79], v[134:137], v[224:227], v[76:79]
	v_mfma_f32_16x16x32_bf16 v[72:75], v[152:155], v[224:227], v[72:75]
	s_setprio 0
	s_setprio 1
	v_mfma_f32_16x16x32_bf16 v[116:119], v[156:159], v[196:199], v[116:119]
	v_mfma_f32_16x16x32_bf16 v[112:115], v[164:167], v[196:199], v[112:115]
	v_mfma_f32_16x16x32_bf16 v[100:103], v[156:159], v[204:207], v[100:103]
	v_mfma_f32_16x16x32_bf16 v[96:99], v[164:167], v[204:207], v[96:99]
	v_mfma_f32_16x16x32_bf16 v[84:87], v[156:159], v[212:215], v[84:87]
	v_mfma_f32_16x16x32_bf16 v[80:83], v[164:167], v[212:215], v[80:83]
	v_mfma_f32_16x16x32_bf16 v[68:71], v[156:159], v[220:223], v[68:71]
	v_mfma_f32_16x16x32_bf16 v[64:67], v[164:167], v[220:223], v[64:67]
	v_mfma_f32_16x16x32_bf16 v[116:119], v[160:163], v[200:203], v[116:119]
	v_mfma_f32_16x16x32_bf16 v[112:115], v[168:171], v[200:203], v[112:115]
	v_mfma_f32_16x16x32_bf16 v[100:103], v[160:163], v[208:211], v[100:103]
	v_mfma_f32_16x16x32_bf16 v[96:99], v[168:171], v[208:211], v[96:99]
	v_mfma_f32_16x16x32_bf16 v[84:87], v[160:163], v[216:219], v[84:87]
	v_mfma_f32_16x16x32_bf16 v[80:83], v[168:171], v[216:219], v[80:83]
	s_setprio 2
	s_barrier
	v_mfma_f32_16x16x32_bf16 v[68:71], v[160:163], v[224:227], v[68:71]
	v_mfma_f32_16x16x32_bf16 v[64:67], v[168:171], v[224:227], v[64:67]
	s_setprio 0
	s_add_i32 s42, s42, s49
	s_mov_b32 m0, s42
	ds_read_b128 v[196:199], v195 offset:16384
	ds_read_b128 v[200:203], v195 offset:17408
	ds_read_b128 v[204:207], v195 offset:18432
	ds_read_b128 v[208:211], v195 offset:19456
	ds_read_b128 v[212:215], v195 offset:20480
	ds_read_b128 v[216:219], v195 offset:21504
	ds_read_b128 v[220:223], v195 offset:22528
	ds_read_b128 v[224:227], v195 offset:23552
	global_load_lds_dwordx4 v138, s[14:15]
	v_mov_b32_e32 v147, v139
	s_add_i32 m0, s42, 0x2000
	v_lshl_add_u64 v[228:229], s[14:15], 0, v[138:139]
	v_lshl_add_u64 v[230:231], s[14:15], 0, v[146:147]
	global_load_lds_dwordx4 v146, s[14:15]
	s_add_u32 s14, s14, s64
	s_addc_u32 s15, s15, s63
	s_add_i32 s42, s43, s49
	s_mov_b32 m0, s42
	v_lshl_add_u64 v[236:237], s[40:41], 0, v[144:145]
	global_load_lds_dwordx4 v138, s[14:15]
	s_add_i32 m0, s42, 0x2000
	v_lshl_add_u64 v[238:239], s[40:41], 0, v[142:143]
	global_load_lds_dwordx4 v146, s[14:15]
	s_mov_b32 m0, s62
	v_lshl_add_u64 v[232:233], s[14:15], 0, v[138:139]
	global_load_lds_dwordx4 v[236:237], off
	s_mov_b32 m0, s65
	v_lshl_add_u64 v[234:235], s[14:15], 0, v[146:147]
	global_load_lds_dwordx4 v[238:239], off
	s_waitcnt vmcnt(8)
	s_waitcnt lgkmcnt(0)
	s_barrier
	s_setprio 1
	s_waitcnt lgkmcnt(0)
	v_mfma_f32_16x16x32_bf16 v[60:63], v[130:133], v[196:199], v[60:63]
	v_mfma_f32_16x16x32_bf16 v[56:59], v[148:151], v[196:199], v[56:59]
	v_mfma_f32_16x16x32_bf16 v[44:47], v[130:133], v[204:207], v[44:47]
	v_mfma_f32_16x16x32_bf16 v[40:43], v[148:151], v[204:207], v[40:43]
	v_mfma_f32_16x16x32_bf16 v[28:31], v[130:133], v[212:215], v[28:31]
	v_mfma_f32_16x16x32_bf16 v[24:27], v[148:151], v[212:215], v[24:27]
	v_mfma_f32_16x16x32_bf16 v[12:15], v[130:133], v[220:223], v[12:15]
	v_mfma_f32_16x16x32_bf16 v[8:11], v[148:151], v[220:223], v[8:11]
	v_mfma_f32_16x16x32_bf16 v[60:63], v[134:137], v[200:203], v[60:63]
	v_mfma_f32_16x16x32_bf16 v[56:59], v[152:155], v[200:203], v[56:59]
	v_mfma_f32_16x16x32_bf16 v[44:47], v[134:137], v[208:211], v[44:47]
	v_mfma_f32_16x16x32_bf16 v[40:43], v[152:155], v[208:211], v[40:43]
	v_mfma_f32_16x16x32_bf16 v[28:31], v[134:137], v[216:219], v[28:31]
	v_mfma_f32_16x16x32_bf16 v[24:27], v[152:155], v[216:219], v[24:27]
	v_mfma_f32_16x16x32_bf16 v[12:15], v[134:137], v[224:227], v[12:15]
	v_mfma_f32_16x16x32_bf16 v[8:11], v[152:155], v[224:227], v[8:11]
	s_setprio 0
	s_setprio 1
	v_mfma_f32_16x16x32_bf16 v[52:55], v[156:159], v[196:199], v[52:55]
	v_mfma_f32_16x16x32_bf16 v[48:51], v[164:167], v[196:199], v[48:51]
	v_mfma_f32_16x16x32_bf16 v[36:39], v[156:159], v[204:207], v[36:39]
	v_mfma_f32_16x16x32_bf16 v[32:35], v[164:167], v[204:207], v[32:35]
	v_mfma_f32_16x16x32_bf16 v[20:23], v[156:159], v[212:215], v[20:23]
	v_mfma_f32_16x16x32_bf16 v[16:19], v[164:167], v[212:215], v[16:19]
	v_mfma_f32_16x16x32_bf16 v[4:7], v[156:159], v[220:223], v[4:7]
	v_mfma_f32_16x16x32_bf16 v[0:3], v[164:167], v[220:223], v[0:3]
	v_mfma_f32_16x16x32_bf16 v[52:55], v[160:163], v[200:203], v[52:55]
	v_mfma_f32_16x16x32_bf16 v[48:51], v[168:171], v[200:203], v[48:51]
	v_mfma_f32_16x16x32_bf16 v[36:39], v[160:163], v[208:211], v[36:39]
	v_mfma_f32_16x16x32_bf16 v[32:35], v[168:171], v[208:211], v[32:35]
	v_mfma_f32_16x16x32_bf16 v[20:23], v[160:163], v[216:219], v[20:23]
	v_mfma_f32_16x16x32_bf16 v[16:19], v[168:171], v[216:219], v[16:19]
	s_setprio 2
	s_barrier
	v_mfma_f32_16x16x32_bf16 v[4:7], v[160:163], v[224:227], v[4:7]
	v_mfma_f32_16x16x32_bf16 v[0:3], v[168:171], v[224:227], v[0:3]
	s_setprio 0
	s_add_i32 s42, 0, 0x18000
	v_add_u32_e32 v147, s42, v194
	s_add_i32 s43, 0, 0x1c000
	ds_read_b128 v[130:133], v147
	ds_read_b128 v[134:137], v147 offset:1024
	ds_read_b128 v[148:151], v147 offset:2048
	ds_read_b128 v[152:155], v147 offset:3072
	v_add_u32_e32 v147, s43, v194
	ds_read_b128 v[156:159], v147
	ds_read_b128 v[160:163], v147 offset:1024
	ds_read_b128 v[164:167], v147 offset:2048
	ds_read_b128 v[168:171], v147 offset:3072
	s_add_u32 s14, s40, 0x40000
	s_addc_u32 s15, s41, 0
	s_mov_b32 m0, s66
	v_lshl_add_u64 v[240:241], s[14:15], 0, v[144:145]
	ds_read_b128 v[196:199], v195 offset:32768
	ds_read_b128 v[200:203], v195 offset:33792
	ds_read_b128 v[204:207], v195 offset:34816
	ds_read_b128 v[208:211], v195 offset:35840
	ds_read_b128 v[212:215], v195 offset:36864
	ds_read_b128 v[216:219], v195 offset:37888
	ds_read_b128 v[220:223], v195 offset:38912
	ds_read_b128 v[224:227], v195 offset:39936
	global_load_lds_dwordx4 v[240:241], off
	v_lshl_add_u64 v[240:241], s[14:15], 0, v[142:143]
	s_mov_b32 m0, s67
	s_nop 0
	global_load_lds_dwordx4 v[240:241], off
	s_waitcnt vmcnt(8)
	s_waitcnt lgkmcnt(0)
	s_barrier
	s_setprio 1
	s_waitcnt lgkmcnt(0)
	v_mfma_f32_16x16x32_bf16 v[124:127], v[130:133], v[196:199], v[124:127]
	v_mfma_f32_16x16x32_bf16 v[120:123], v[148:151], v[196:199], v[120:123]
	v_mfma_f32_16x16x32_bf16 v[108:111], v[130:133], v[204:207], v[108:111]
	v_mfma_f32_16x16x32_bf16 v[104:107], v[148:151], v[204:207], v[104:107]
	v_mfma_f32_16x16x32_bf16 v[92:95], v[130:133], v[212:215], v[92:95]
	v_mfma_f32_16x16x32_bf16 v[88:91], v[148:151], v[212:215], v[88:91]
	v_mfma_f32_16x16x32_bf16 v[76:79], v[130:133], v[220:223], v[76:79]
	v_mfma_f32_16x16x32_bf16 v[72:75], v[148:151], v[220:223], v[72:75]
	v_mfma_f32_16x16x32_bf16 v[124:127], v[134:137], v[200:203], v[124:127]
	v_mfma_f32_16x16x32_bf16 v[120:123], v[152:155], v[200:203], v[120:123]
	v_mfma_f32_16x16x32_bf16 v[108:111], v[134:137], v[208:211], v[108:111]
	v_mfma_f32_16x16x32_bf16 v[104:107], v[152:155], v[208:211], v[104:107]
	v_mfma_f32_16x16x32_bf16 v[92:95], v[134:137], v[216:219], v[92:95]
	v_mfma_f32_16x16x32_bf16 v[88:91], v[152:155], v[216:219], v[88:91]
	v_mfma_f32_16x16x32_bf16 v[76:79], v[134:137], v[224:227], v[76:79]
	v_mfma_f32_16x16x32_bf16 v[72:75], v[152:155], v[224:227], v[72:75]
	s_setprio 0
	s_setprio 1
	v_mfma_f32_16x16x32_bf16 v[116:119], v[156:159], v[196:199], v[116:119]
	v_mfma_f32_16x16x32_bf16 v[112:115], v[164:167], v[196:199], v[112:115]
	v_mfma_f32_16x16x32_bf16 v[100:103], v[156:159], v[204:207], v[100:103]
	v_mfma_f32_16x16x32_bf16 v[96:99], v[164:167], v[204:207], v[96:99]
	v_mfma_f32_16x16x32_bf16 v[84:87], v[156:159], v[212:215], v[84:87]
	v_mfma_f32_16x16x32_bf16 v[80:83], v[164:167], v[212:215], v[80:83]
	v_mfma_f32_16x16x32_bf16 v[68:71], v[156:159], v[220:223], v[68:71]
	v_mfma_f32_16x16x32_bf16 v[64:67], v[164:167], v[220:223], v[64:67]
	v_mfma_f32_16x16x32_bf16 v[116:119], v[160:163], v[200:203], v[116:119]
	v_mfma_f32_16x16x32_bf16 v[112:115], v[168:171], v[200:203], v[112:115]
	v_mfma_f32_16x16x32_bf16 v[100:103], v[160:163], v[208:211], v[100:103]
	v_mfma_f32_16x16x32_bf16 v[96:99], v[168:171], v[208:211], v[96:99]
	v_mfma_f32_16x16x32_bf16 v[84:87], v[160:163], v[216:219], v[84:87]
	v_mfma_f32_16x16x32_bf16 v[80:83], v[168:171], v[216:219], v[80:83]
	s_setprio 2
	s_barrier
	v_mfma_f32_16x16x32_bf16 v[68:71], v[160:163], v[224:227], v[68:71]
	v_mfma_f32_16x16x32_bf16 v[64:67], v[168:171], v[224:227], v[64:67]
	s_setprio 0
	s_add_i32 s14, s42, s49
	v_lshl_add_u64 v[228:229], v[228:229], 0, s[16:17]
	s_mov_b32 m0, s14
	ds_read_b128 v[196:199], v195 offset:49152
	ds_read_b128 v[200:203], v195 offset:50176
	ds_read_b128 v[204:207], v195 offset:51200
	ds_read_b128 v[208:211], v195 offset:52224
	ds_read_b128 v[212:215], v195 offset:53248
	ds_read_b128 v[216:219], v195 offset:54272
	ds_read_b128 v[220:223], v195 offset:55296
	ds_read_b128 v[224:227], v195 offset:56320
	global_load_lds_dwordx4 v[228:229], off
	v_lshl_add_u64 v[228:229], v[230:231], 0, s[16:17]
	s_add_i32 m0, s14, 0x2000
	s_add_i32 s14, s43, s49
	global_load_lds_dwordx4 v[228:229], off
	v_lshl_add_u64 v[228:229], v[232:233], 0, s[16:17]
	s_mov_b32 m0, s14
	s_nop 0
	global_load_lds_dwordx4 v[228:229], off
	v_lshl_add_u64 v[228:229], v[234:235], 0, s[16:17]
	s_add_i32 m0, s14, 0x2000
	s_nop 0
	global_load_lds_dwordx4 v[228:229], off
	v_lshl_add_u64 v[228:229], v[236:237], 0, s[16:17]
	s_mov_b32 m0, s72
	s_nop 0
	global_load_lds_dwordx4 v[228:229], off
	v_lshl_add_u64 v[228:229], v[238:239], 0, s[16:17]
	s_mov_b32 m0, s73
	s_nop 0
	global_load_lds_dwordx4 v[228:229], off
	s_waitcnt vmcnt(8)
	s_waitcnt lgkmcnt(0)
	s_barrier
	s_setprio 1
	s_waitcnt lgkmcnt(0)
	v_mfma_f32_16x16x32_bf16 v[60:63], v[130:133], v[196:199], v[60:63]
	v_mfma_f32_16x16x32_bf16 v[56:59], v[148:151], v[196:199], v[56:59]
	v_mfma_f32_16x16x32_bf16 v[44:47], v[130:133], v[204:207], v[44:47]
	v_mfma_f32_16x16x32_bf16 v[40:43], v[148:151], v[204:207], v[40:43]
	v_mfma_f32_16x16x32_bf16 v[28:31], v[130:133], v[212:215], v[28:31]
	v_mfma_f32_16x16x32_bf16 v[24:27], v[148:151], v[212:215], v[24:27]
	v_mfma_f32_16x16x32_bf16 v[12:15], v[130:133], v[220:223], v[12:15]
	v_mfma_f32_16x16x32_bf16 v[8:11], v[148:151], v[220:223], v[8:11]
	v_mfma_f32_16x16x32_bf16 v[60:63], v[134:137], v[200:203], v[60:63]
	v_mfma_f32_16x16x32_bf16 v[56:59], v[152:155], v[200:203], v[56:59]
	v_mfma_f32_16x16x32_bf16 v[44:47], v[134:137], v[208:211], v[44:47]
	v_mfma_f32_16x16x32_bf16 v[40:43], v[152:155], v[208:211], v[40:43]
	v_mfma_f32_16x16x32_bf16 v[28:31], v[134:137], v[216:219], v[28:31]
	v_mfma_f32_16x16x32_bf16 v[24:27], v[152:155], v[216:219], v[24:27]
	v_mfma_f32_16x16x32_bf16 v[12:15], v[134:137], v[224:227], v[12:15]
	v_mfma_f32_16x16x32_bf16 v[8:11], v[152:155], v[224:227], v[8:11]
	s_setprio 0
	s_setprio 1
	v_mfma_f32_16x16x32_bf16 v[52:55], v[156:159], v[196:199], v[52:55]
	v_mfma_f32_16x16x32_bf16 v[48:51], v[164:167], v[196:199], v[48:51]
	v_mfma_f32_16x16x32_bf16 v[36:39], v[156:159], v[204:207], v[36:39]
	v_mfma_f32_16x16x32_bf16 v[32:35], v[164:167], v[204:207], v[32:35]
	v_mfma_f32_16x16x32_bf16 v[20:23], v[156:159], v[212:215], v[20:23]
	v_mfma_f32_16x16x32_bf16 v[16:19], v[164:167], v[212:215], v[16:19]
	v_mfma_f32_16x16x32_bf16 v[4:7], v[156:159], v[220:223], v[4:7]
	v_mfma_f32_16x16x32_bf16 v[0:3], v[164:167], v[220:223], v[0:3]
	v_mfma_f32_16x16x32_bf16 v[52:55], v[160:163], v[200:203], v[52:55]
	v_mfma_f32_16x16x32_bf16 v[48:51], v[168:171], v[200:203], v[48:51]
	v_mfma_f32_16x16x32_bf16 v[36:39], v[160:163], v[208:211], v[36:39]
	v_mfma_f32_16x16x32_bf16 v[32:35], v[168:171], v[208:211], v[32:35]
	v_mfma_f32_16x16x32_bf16 v[20:23], v[160:163], v[216:219], v[20:23]
	v_mfma_f32_16x16x32_bf16 v[16:19], v[168:171], v[216:219], v[16:19]
	s_setprio 2
	s_barrier
	v_mfma_f32_16x16x32_bf16 v[4:7], v[160:163], v[224:227], v[4:7]
	v_mfma_f32_16x16x32_bf16 v[0:3], v[168:171], v[224:227], v[0:3]
	s_setprio 0
	s_add_i32 s89, s89, 2
	s_add_u32 s12, s12, 0x100
	s_addc_u32 s13, s13, 0
	s_add_u32 s87, s87, 0x100
	s_addc_u32 s88, s88, 0
	s_cmp_gt_u32 s89, 13
	s_cbranch_scc0 .LBB0_965
	s_and_b64 vcc, exec, s[26:27]
	s_cbranch_vccz .LBB0_968
	s_barrier

.LBB0_1511:
	v_add_u32_e32 v162, s50, v148
	v_add_u32_e32 v178, s51, v148
	s_add_u32 s34, s16, s26
	ds_read_b128 v[150:153], v162
	ds_read_b128 v[154:157], v162 offset:1024
	ds_read_b128 v[158:161], v162 offset:2048
	ds_read_b128 v[162:165], v162 offset:3072
	ds_read_b128 v[166:169], v178
	ds_read_b128 v[170:173], v178 offset:1024
	ds_read_b128 v[174:177], v178 offset:2048
	ds_read_b128 v[178:181], v178 offset:3072
	s_addc_u32 s35, s17, s27
	s_add_u32 s34, s34, 0x100
	s_addc_u32 s35, s35, 0
	s_add_u32 s57, s21, s26
	s_addc_u32 s58, s55, s27
	s_cmpk_eq_i32 s26, 0xf00
	s_cselect_b32 s37, s29, s35
	s_cselect_b32 s36, s28, s34
	s_cselect_b32 s35, s31, s58
	s_cselect_b32 s34, s30, s57
	v_lshl_add_u64 v[214:215], v[144:145], 0, s[26:27]
	s_add_i32 m0, s13, 0xc000
	ds_read_b128 v[182:185], v149
	ds_read_b128 v[186:189], v149 offset:1024
	ds_read_b128 v[190:193], v149 offset:2048
	ds_read_b128 v[194:197], v149 offset:3072
	ds_read_b128 v[198:201], v149 offset:4096
	ds_read_b128 v[202:205], v149 offset:5120
	ds_read_b128 v[206:209], v149 offset:6144
	ds_read_b128 v[210:213], v149 offset:7168
	global_load_lds_dwordx4 v[214:215], off
	v_lshl_add_u64 v[214:215], v[146:147], 0, s[26:27]
	s_add_i32 m0, s13, 0xe000
	s_nop 0
	global_load_lds_dwordx4 v[214:215], off
	s_waitcnt vmcnt(8)
	s_waitcnt lgkmcnt(0)
	s_barrier
	s_setprio 1
	s_waitcnt lgkmcnt(0)
	v_mfma_f32_16x16x32_bf16 v[128:131], v[150:153], v[182:185], v[128:131]
	v_mfma_f32_16x16x32_bf16 v[124:127], v[158:161], v[182:185], v[124:127]
	v_mfma_f32_16x16x32_bf16 v[116:119], v[150:153], v[190:193], v[116:119]
	v_mfma_f32_16x16x32_bf16 v[108:111], v[158:161], v[190:193], v[108:111]
	v_mfma_f32_16x16x32_bf16 v[100:103], v[150:153], v[198:201], v[100:103]
	v_mfma_f32_16x16x32_bf16 v[92:95], v[158:161], v[198:201], v[92:95]
	v_mfma_f32_16x16x32_bf16 v[84:87], v[150:153], v[206:209], v[84:87]
	v_mfma_f32_16x16x32_bf16 v[76:79], v[158:161], v[206:209], v[76:79]
	v_mfma_f32_16x16x32_bf16 v[128:131], v[154:157], v[186:189], v[128:131]
	v_mfma_f32_16x16x32_bf16 v[124:127], v[162:165], v[186:189], v[124:127]
	v_mfma_f32_16x16x32_bf16 v[116:119], v[154:157], v[194:197], v[116:119]
	v_mfma_f32_16x16x32_bf16 v[108:111], v[162:165], v[194:197], v[108:111]
	v_mfma_f32_16x16x32_bf16 v[100:103], v[154:157], v[202:205], v[100:103]
	v_mfma_f32_16x16x32_bf16 v[92:95], v[162:165], v[202:205], v[92:95]
	v_mfma_f32_16x16x32_bf16 v[84:87], v[154:157], v[210:213], v[84:87]
	v_mfma_f32_16x16x32_bf16 v[76:79], v[162:165], v[210:213], v[76:79]
	s_setprio 0
	s_setprio 1
	v_mfma_f32_16x16x32_bf16 v[120:123], v[166:169], v[182:185], v[120:123]
	v_mfma_f32_16x16x32_bf16 v[112:115], v[174:177], v[182:185], v[112:115]
	v_mfma_f32_16x16x32_bf16 v[104:107], v[166:169], v[190:193], v[104:107]
	v_mfma_f32_16x16x32_bf16 v[96:99], v[174:177], v[190:193], v[96:99]
	v_mfma_f32_16x16x32_bf16 v[88:91], v[166:169], v[198:201], v[88:91]
	v_mfma_f32_16x16x32_bf16 v[80:83], v[174:177], v[198:201], v[80:83]
	v_mfma_f32_16x16x32_bf16 v[72:75], v[166:169], v[206:209], v[72:75]
	v_mfma_f32_16x16x32_bf16 v[68:71], v[174:177], v[206:209], v[68:71]
	v_mfma_f32_16x16x32_bf16 v[120:123], v[170:173], v[186:189], v[120:123]
	v_mfma_f32_16x16x32_bf16 v[112:115], v[178:181], v[186:189], v[112:115]
	v_mfma_f32_16x16x32_bf16 v[104:107], v[170:173], v[194:197], v[104:107]
	v_mfma_f32_16x16x32_bf16 v[96:99], v[178:181], v[194:197], v[96:99]
	v_mfma_f32_16x16x32_bf16 v[88:91], v[170:173], v[202:205], v[88:91]
	v_mfma_f32_16x16x32_bf16 v[80:83], v[178:181], v[202:205], v[80:83]
	s_setprio 2
	s_barrier
	v_mfma_f32_16x16x32_bf16 v[72:75], v[170:173], v[210:213], v[72:75]
	v_mfma_f32_16x16x32_bf16 v[68:71], v[178:181], v[210:213], v[68:71]
	s_setprio 0
	s_add_i32 s57, s50, s42
	v_lshl_add_u64 v[214:215], s[34:35], 0, v[2:3]
	s_mov_b32 m0, s57
	ds_read_b128 v[182:185], v149 offset:16384
	ds_read_b128 v[186:189], v149 offset:17408
	ds_read_b128 v[190:193], v149 offset:18432
	ds_read_b128 v[194:197], v149 offset:19456
	ds_read_b128 v[198:201], v149 offset:20480
	ds_read_b128 v[202:205], v149 offset:21504
	ds_read_b128 v[206:209], v149 offset:22528
	ds_read_b128 v[210:213], v149 offset:23552
	global_load_lds_dwordx4 v[214:215], off
	s_add_i32 m0, s57, 0x2000
	s_add_u32 s58, s34, 0x80000
	v_lshl_add_u64 v[216:217], s[34:35], 0, v[134:135]
	s_addc_u32 s59, s35, 0
	s_add_i32 s57, s51, s42
	global_load_lds_dwordx4 v[216:217], off
	v_lshl_add_u64 v[218:219], s[58:59], 0, v[2:3]
	s_mov_b32 m0, s57
	v_lshl_add_u64 v[220:221], s[36:37], 0, v[132:133]
	global_load_lds_dwordx4 v[218:219], off
	v_lshl_add_u64 v[218:219], s[58:59], 0, v[134:135]
	s_add_i32 m0, s57, 0x2000
	s_nop 0
	global_load_lds_dwordx4 v[218:219], off
	v_lshl_add_u64 v[218:219], s[36:37], 0, v[0:1]
	s_mov_b32 m0, s13
	s_nop 0
	global_load_lds_dwordx4 v[218:219], off
	s_mov_b32 m0, s43
	s_nop 0
	global_load_lds_dwordx4 v[220:221], off
	s_waitcnt vmcnt(8)
	s_waitcnt lgkmcnt(0)
	s_barrier
	s_setprio 1
	s_waitcnt lgkmcnt(0)
	v_mfma_f32_16x16x32_bf16 v[64:67], v[150:153], v[182:185], v[64:67]
	v_mfma_f32_16x16x32_bf16 v[60:63], v[158:161], v[182:185], v[60:63]
	v_mfma_f32_16x16x32_bf16 v[52:55], v[150:153], v[190:193], v[52:55]
	v_mfma_f32_16x16x32_bf16 v[44:47], v[158:161], v[190:193], v[44:47]
	v_mfma_f32_16x16x32_bf16 v[36:39], v[150:153], v[198:201], v[36:39]
	v_mfma_f32_16x16x32_bf16 v[28:31], v[158:161], v[198:201], v[28:31]
	v_mfma_f32_16x16x32_bf16 v[20:23], v[150:153], v[206:209], v[20:23]
	v_mfma_f32_16x16x32_bf16 v[12:15], v[158:161], v[206:209], v[12:15]
	v_mfma_f32_16x16x32_bf16 v[64:67], v[154:157], v[186:189], v[64:67]
	v_mfma_f32_16x16x32_bf16 v[60:63], v[162:165], v[186:189], v[60:63]
	v_mfma_f32_16x16x32_bf16 v[52:55], v[154:157], v[194:197], v[52:55]
	v_mfma_f32_16x16x32_bf16 v[44:47], v[162:165], v[194:197], v[44:47]
	v_mfma_f32_16x16x32_bf16 v[36:39], v[154:157], v[202:205], v[36:39]
	v_mfma_f32_16x16x32_bf16 v[28:31], v[162:165], v[202:205], v[28:31]
	v_mfma_f32_16x16x32_bf16 v[20:23], v[154:157], v[210:213], v[20:23]
	v_mfma_f32_16x16x32_bf16 v[12:15], v[162:165], v[210:213], v[12:15]
	s_setprio 0
	s_setprio 1
	v_mfma_f32_16x16x32_bf16 v[56:59], v[166:169], v[182:185], v[56:59]
	v_mfma_f32_16x16x32_bf16 v[48:51], v[174:177], v[182:185], v[48:51]
	v_mfma_f32_16x16x32_bf16 v[40:43], v[166:169], v[190:193], v[40:43]
	v_mfma_f32_16x16x32_bf16 v[32:35], v[174:177], v[190:193], v[32:35]
	v_mfma_f32_16x16x32_bf16 v[24:27], v[166:169], v[198:201], v[24:27]
	v_mfma_f32_16x16x32_bf16 v[16:19], v[174:177], v[198:201], v[16:19]
	v_mfma_f32_16x16x32_bf16 v[8:11], v[166:169], v[206:209], v[8:11]
	v_mfma_f32_16x16x32_bf16 v[4:7], v[174:177], v[206:209], v[4:7]
	v_mfma_f32_16x16x32_bf16 v[56:59], v[170:173], v[186:189], v[56:59]
	v_mfma_f32_16x16x32_bf16 v[48:51], v[178:181], v[186:189], v[48:51]
	v_mfma_f32_16x16x32_bf16 v[40:43], v[170:173], v[194:197], v[40:43]
	v_mfma_f32_16x16x32_bf16 v[32:35], v[178:181], v[194:197], v[32:35]
	v_mfma_f32_16x16x32_bf16 v[24:27], v[170:173], v[202:205], v[24:27]
	v_mfma_f32_16x16x32_bf16 v[16:19], v[178:181], v[202:205], v[16:19]
	s_setprio 2
	s_barrier
	v_mfma_f32_16x16x32_bf16 v[8:11], v[170:173], v[210:213], v[8:11]
	v_mfma_f32_16x16x32_bf16 v[4:7], v[178:181], v[210:213], v[4:7]
	s_setprio 0
	s_add_i32 s57, 0, 0x18000
	s_add_i32 s58, 0, 0x1c000
	v_add_u32_e32 v162, s57, v148
	v_add_u32_e32 v178, s58, v148
	ds_read_b128 v[150:153], v162
	ds_read_b128 v[154:157], v162 offset:1024
	ds_read_b128 v[158:161], v162 offset:2048
	ds_read_b128 v[162:165], v162 offset:3072
	ds_read_b128 v[166:169], v178
	ds_read_b128 v[170:173], v178 offset:1024
	ds_read_b128 v[174:177], v178 offset:2048
	ds_read_b128 v[178:181], v178 offset:3072
	s_add_u32 s36, s36, 0x80000
	s_addc_u32 s37, s37, 0
	s_mov_b32 m0, s45
	v_lshl_add_u64 v[222:223], s[36:37], 0, v[0:1]
	ds_read_b128 v[182:185], v149 offset:32768
	ds_read_b128 v[186:189], v149 offset:33792
	ds_read_b128 v[190:193], v149 offset:34816
	ds_read_b128 v[194:197], v149 offset:35840
	ds_read_b128 v[198:201], v149 offset:36864
	ds_read_b128 v[202:205], v149 offset:37888
	ds_read_b128 v[206:209], v149 offset:38912
	ds_read_b128 v[210:213], v149 offset:39936
	global_load_lds_dwordx4 v[222:223], off
	v_lshl_add_u64 v[222:223], s[36:37], 0, v[132:133]
	s_mov_b32 m0, s46
	s_nop 0
	global_load_lds_dwordx4 v[222:223], off
	s_waitcnt vmcnt(8)
	s_waitcnt lgkmcnt(0)
	s_barrier
	s_setprio 1
	s_waitcnt lgkmcnt(0)
	v_mfma_f32_16x16x32_bf16 v[128:131], v[150:153], v[182:185], v[128:131]
	v_mfma_f32_16x16x32_bf16 v[124:127], v[158:161], v[182:185], v[124:127]
	v_mfma_f32_16x16x32_bf16 v[116:119], v[150:153], v[190:193], v[116:119]
	v_mfma_f32_16x16x32_bf16 v[108:111], v[158:161], v[190:193], v[108:111]
	v_mfma_f32_16x16x32_bf16 v[100:103], v[150:153], v[198:201], v[100:103]
	v_mfma_f32_16x16x32_bf16 v[92:95], v[158:161], v[198:201], v[92:95]
	v_mfma_f32_16x16x32_bf16 v[84:87], v[150:153], v[206:209], v[84:87]
	v_mfma_f32_16x16x32_bf16 v[76:79], v[158:161], v[206:209], v[76:79]
	v_mfma_f32_16x16x32_bf16 v[128:131], v[154:157], v[186:189], v[128:131]
	v_mfma_f32_16x16x32_bf16 v[124:127], v[162:165], v[186:189], v[124:127]
	v_mfma_f32_16x16x32_bf16 v[116:119], v[154:157], v[194:197], v[116:119]
	v_mfma_f32_16x16x32_bf16 v[108:111], v[162:165], v[194:197], v[108:111]
	v_mfma_f32_16x16x32_bf16 v[100:103], v[154:157], v[202:205], v[100:103]
	v_mfma_f32_16x16x32_bf16 v[92:95], v[162:165], v[202:205], v[92:95]
	v_mfma_f32_16x16x32_bf16 v[84:87], v[154:157], v[210:213], v[84:87]
	v_mfma_f32_16x16x32_bf16 v[76:79], v[162:165], v[210:213], v[76:79]
	s_setprio 0
	s_setprio 1
	v_mfma_f32_16x16x32_bf16 v[120:123], v[166:169], v[182:185], v[120:123]
	v_mfma_f32_16x16x32_bf16 v[112:115], v[174:177], v[182:185], v[112:115]
	v_mfma_f32_16x16x32_bf16 v[104:107], v[166:169], v[190:193], v[104:107]
	v_mfma_f32_16x16x32_bf16 v[96:99], v[174:177], v[190:193], v[96:99]
	v_mfma_f32_16x16x32_bf16 v[88:91], v[166:169], v[198:201], v[88:91]
	v_mfma_f32_16x16x32_bf16 v[80:83], v[174:177], v[198:201], v[80:83]
	v_mfma_f32_16x16x32_bf16 v[72:75], v[166:169], v[206:209], v[72:75]
	v_mfma_f32_16x16x32_bf16 v[68:71], v[174:177], v[206:209], v[68:71]
	v_mfma_f32_16x16x32_bf16 v[120:123], v[170:173], v[186:189], v[120:123]
	v_mfma_f32_16x16x32_bf16 v[112:115], v[178:181], v[186:189], v[112:115]
	v_mfma_f32_16x16x32_bf16 v[104:107], v[170:173], v[194:197], v[104:107]
	v_mfma_f32_16x16x32_bf16 v[96:99], v[178:181], v[194:197], v[96:99]
	v_mfma_f32_16x16x32_bf16 v[88:91], v[170:173], v[202:205], v[88:91]
	v_mfma_f32_16x16x32_bf16 v[80:83], v[178:181], v[202:205], v[80:83]
	s_setprio 2
	s_barrier
	v_mfma_f32_16x16x32_bf16 v[72:75], v[170:173], v[210:213], v[72:75]
	v_mfma_f32_16x16x32_bf16 v[68:71], v[178:181], v[210:213], v[68:71]
	s_setprio 0
	s_add_i32 s36, s57, s42
	v_lshl_add_u64 v[214:215], v[214:215], 0, s[18:19]
	s_mov_b32 m0, s36
	ds_read_b128 v[182:185], v149 offset:49152
	ds_read_b128 v[186:189], v149 offset:50176
	ds_read_b128 v[190:193], v149 offset:51200
	ds_read_b128 v[194:197], v149 offset:52224
	ds_read_b128 v[198:201], v149 offset:53248
	ds_read_b128 v[202:205], v149 offset:54272
	ds_read_b128 v[206:209], v149 offset:55296
	ds_read_b128 v[210:213], v149 offset:56320
	global_load_lds_dwordx4 v[214:215], off
	s_add_i32 m0, s36, 0x2000
	s_add_u32 s34, s34, 0x80080
	v_lshl_add_u64 v[214:215], v[216:217], 0, s[18:19]
	s_addc_u32 s35, s35, 0
	s_add_i32 s36, s58, s42
	global_load_lds_dwordx4 v[214:215], off
	v_lshl_add_u64 v[214:215], s[34:35], 0, v[2:3]
	s_mov_b32 m0, s36
	s_nop 0
	global_load_lds_dwordx4 v[214:215], off
	v_lshl_add_u64 v[214:215], s[34:35], 0, v[134:135]
	s_add_i32 m0, s36, 0x2000
	s_nop 0
	global_load_lds_dwordx4 v[214:215], off
	v_lshl_add_u64 v[214:215], v[218:219], 0, s[18:19]
	s_mov_b32 m0, s48
	s_nop 0
	global_load_lds_dwordx4 v[214:215], off
	v_lshl_add_u64 v[214:215], v[220:221], 0, s[18:19]
	s_mov_b32 m0, s49
	s_nop 0
	global_load_lds_dwordx4 v[214:215], off
	s_waitcnt vmcnt(8)
	s_waitcnt lgkmcnt(0)
	s_barrier
	s_setprio 1
	s_waitcnt lgkmcnt(0)
	v_mfma_f32_16x16x32_bf16 v[64:67], v[150:153], v[182:185], v[64:67]
	v_mfma_f32_16x16x32_bf16 v[60:63], v[158:161], v[182:185], v[60:63]
	v_mfma_f32_16x16x32_bf16 v[52:55], v[150:153], v[190:193], v[52:55]
	v_mfma_f32_16x16x32_bf16 v[44:47], v[158:161], v[190:193], v[44:47]
	v_mfma_f32_16x16x32_bf16 v[36:39], v[150:153], v[198:201], v[36:39]
	v_mfma_f32_16x16x32_bf16 v[28:31], v[158:161], v[198:201], v[28:31]
	v_mfma_f32_16x16x32_bf16 v[20:23], v[150:153], v[206:209], v[20:23]
	v_mfma_f32_16x16x32_bf16 v[12:15], v[158:161], v[206:209], v[12:15]
	v_mfma_f32_16x16x32_bf16 v[64:67], v[154:157], v[186:189], v[64:67]
	v_mfma_f32_16x16x32_bf16 v[60:63], v[162:165], v[186:189], v[60:63]
	v_mfma_f32_16x16x32_bf16 v[52:55], v[154:157], v[194:197], v[52:55]
	v_mfma_f32_16x16x32_bf16 v[44:47], v[162:165], v[194:197], v[44:47]
	v_mfma_f32_16x16x32_bf16 v[36:39], v[154:157], v[202:205], v[36:39]
	v_mfma_f32_16x16x32_bf16 v[28:31], v[162:165], v[202:205], v[28:31]
	v_mfma_f32_16x16x32_bf16 v[20:23], v[154:157], v[210:213], v[20:23]
	v_mfma_f32_16x16x32_bf16 v[12:15], v[162:165], v[210:213], v[12:15]
	s_setprio 0
	s_setprio 1
	v_mfma_f32_16x16x32_bf16 v[56:59], v[166:169], v[182:185], v[56:59]
	v_mfma_f32_16x16x32_bf16 v[48:51], v[174:177], v[182:185], v[48:51]
	v_mfma_f32_16x16x32_bf16 v[40:43], v[166:169], v[190:193], v[40:43]
	v_mfma_f32_16x16x32_bf16 v[32:35], v[174:177], v[190:193], v[32:35]
	v_mfma_f32_16x16x32_bf16 v[24:27], v[166:169], v[198:201], v[24:27]
	v_mfma_f32_16x16x32_bf16 v[16:19], v[174:177], v[198:201], v[16:19]
	v_mfma_f32_16x16x32_bf16 v[8:11], v[166:169], v[206:209], v[8:11]
	v_mfma_f32_16x16x32_bf16 v[4:7], v[174:177], v[206:209], v[4:7]
	v_mfma_f32_16x16x32_bf16 v[56:59], v[170:173], v[186:189], v[56:59]
	v_mfma_f32_16x16x32_bf16 v[48:51], v[178:181], v[186:189], v[48:51]
	v_mfma_f32_16x16x32_bf16 v[40:43], v[170:173], v[194:197], v[40:43]
	v_mfma_f32_16x16x32_bf16 v[32:35], v[178:181], v[194:197], v[32:35]
	v_mfma_f32_16x16x32_bf16 v[24:27], v[170:173], v[202:205], v[24:27]
	v_mfma_f32_16x16x32_bf16 v[16:19], v[178:181], v[202:205], v[16:19]
	s_setprio 2
	s_barrier
	v_mfma_f32_16x16x32_bf16 v[8:11], v[170:173], v[210:213], v[8:11]
	v_mfma_f32_16x16x32_bf16 v[4:7], v[178:181], v[210:213], v[4:7]
	s_setprio 0
	s_add_i32 s56, s56, 2
	s_add_u32 s26, s26, 0x100
	s_addc_u32 s27, s27, 0
	s_cmp_gt_u32 s56, 29
	s_cbranch_scc0 .LBB0_1511
	s_add_u32 s26, s21, 0xffffff00
	s_addc_u32 s27, s55, -1
	s_andn2_b64 vcc, exec, s[4:5]
	s_cbranch_vccnz .LBB0_1503
	v_mov_b32_e32 v4, 0
	s_mov_b32 s14, s53
	s_mov_b32 s12, s20
	s_mov_b64 s[26:27], s[24:25]
	s_mov_b64 s[16:17], s[22:23]
	s_mov_b32 s47, s54
	v_mov_b32_e32 v5, v4
	v_mov_b32_e32 v6, v4
	v_mov_b32_e32 v7, v4
	v_mov_b32_e32 v8, v4
	v_mov_b32_e32 v9, v4
	v_mov_b32_e32 v10, v4
	v_mov_b32_e32 v11, v4
	v_mov_b32_e32 v16, v4
	v_mov_b32_e32 v17, v4
	v_mov_b32_e32 v18, v4
	v_mov_b32_e32 v19, v4
	v_mov_b32_e32 v24, v4
	v_mov_b32_e32 v25, v4
	v_mov_b32_e32 v26, v4
	v_mov_b32_e32 v27, v4
	v_mov_b32_e32 v32, v4
	v_mov_b32_e32 v33, v4
	v_mov_b32_e32 v34, v4
	v_mov_b32_e32 v35, v4
	v_mov_b32_e32 v40, v4
	v_mov_b32_e32 v41, v4
	v_mov_b32_e32 v42, v4
	v_mov_b32_e32 v43, v4
	v_mov_b32_e32 v48, v4
	v_mov_b32_e32 v49, v4
	v_mov_b32_e32 v50, v4
	v_mov_b32_e32 v51, v4
	v_mov_b32_e32 v56, v4
	v_mov_b32_e32 v57, v4
	v_mov_b32_e32 v58, v4
	v_mov_b32_e32 v59, v4
	v_mov_b32_e32 v12, v4
	v_mov_b32_e32 v13, v4
	v_mov_b32_e32 v14, v4
	v_mov_b32_e32 v15, v4
	v_mov_b32_e32 v20, v4
	v_mov_b32_e32 v21, v4
	v_mov_b32_e32 v22, v4
	v_mov_b32_e32 v23, v4
	v_mov_b32_e32 v28, v4
	v_mov_b32_e32 v29, v4
	v_mov_b32_e32 v30, v4
	v_mov_b32_e32 v31, v4
	v_mov_b32_e32 v36, v4
	v_mov_b32_e32 v37, v4
	v_mov_b32_e32 v38, v4
	v_mov_b32_e32 v39, v4
	v_mov_b32_e32 v44, v4
	v_mov_b32_e32 v45, v4
	v_mov_b32_e32 v46, v4
	v_mov_b32_e32 v47, v4
	v_mov_b32_e32 v52, v4
	v_mov_b32_e32 v53, v4
	v_mov_b32_e32 v54, v4
	v_mov_b32_e32 v55, v4
	v_mov_b32_e32 v60, v4
	v_mov_b32_e32 v61, v4
	v_mov_b32_e32 v62, v4
	v_mov_b32_e32 v63, v4
	v_mov_b32_e32 v64, v4
	v_mov_b32_e32 v65, v4
	v_mov_b32_e32 v66, v4
	v_mov_b32_e32 v67, v4
	v_mov_b32_e32 v68, v4
	v_mov_b32_e32 v69, v4
	v_mov_b32_e32 v70, v4
	v_mov_b32_e32 v71, v4
	v_mov_b32_e32 v72, v4
	v_mov_b32_e32 v73, v4
	v_mov_b32_e32 v74, v4
	v_mov_b32_e32 v75, v4
	v_mov_b32_e32 v80, v4
	v_mov_b32_e32 v81, v4
	v_mov_b32_e32 v82, v4
	v_mov_b32_e32 v83, v4
	v_mov_b32_e32 v88, v4
	v_mov_b32_e32 v89, v4
	v_mov_b32_e32 v90, v4
	v_mov_b32_e32 v91, v4
	v_mov_b32_e32 v96, v4
	v_mov_b32_e32 v97, v4
	v_mov_b32_e32 v98, v4
	v_mov_b32_e32 v99, v4
	v_mov_b32_e32 v104, v4
	v_mov_b32_e32 v105, v4
	v_mov_b32_e32 v106, v4
	v_mov_b32_e32 v107, v4
	v_mov_b32_e32 v112, v4
	v_mov_b32_e32 v113, v4
	v_mov_b32_e32 v114, v4
	v_mov_b32_e32 v115, v4
	v_mov_b32_e32 v120, v4
	v_mov_b32_e32 v121, v4
	v_mov_b32_e32 v122, v4
	v_mov_b32_e32 v123, v4
	v_mov_b32_e32 v76, v4
	v_mov_b32_e32 v77, v4
	v_mov_b32_e32 v78, v4
	v_mov_b32_e32 v79, v4
	v_mov_b32_e32 v84, v4
	v_mov_b32_e32 v85, v4
	v_mov_b32_e32 v86, v4
	v_mov_b32_e32 v87, v4
	v_mov_b32_e32 v92, v4
	v_mov_b32_e32 v93, v4
	v_mov_b32_e32 v94, v4
	v_mov_b32_e32 v95, v4
	v_mov_b32_e32 v100, v4
	v_mov_b32_e32 v101, v4
	v_mov_b32_e32 v102, v4
	v_mov_b32_e32 v103, v4
	v_mov_b32_e32 v108, v4
	v_mov_b32_e32 v109, v4
	v_mov_b32_e32 v110, v4
	v_mov_b32_e32 v111, v4
	v_mov_b32_e32 v116, v4
	v_mov_b32_e32 v117, v4
	v_mov_b32_e32 v118, v4
	v_mov_b32_e32 v119, v4
	v_mov_b32_e32 v124, v4
	v_mov_b32_e32 v125, v4
	v_mov_b32_e32 v126, v4
	v_mov_b32_e32 v127, v4
	v_mov_b32_e32 v128, v4
	v_mov_b32_e32 v129, v4
	v_mov_b32_e32 v130, v4
	v_mov_b32_e32 v131, v4
	s_branch .LBB0_1503
